# combined: K-sweep alternation, store-counted peel waits, early leading-half epilogue, attention reorder, rope/final/GLA0 latency hoists on top of the SwiGLU regeneration
# speedup vs baseline: 1.0021x; 1.0021x over previous
.Lg131_noy:
	ds_read_b128 v[152:155], v149
	ds_read_b128 v[156:159], v149 offset:1024
	ds_read_b128 v[160:163], v149 offset:2048
	ds_read_b128 v[164:167], v149 offset:3072
	s_add_u32 s26, s20, 0xfffc0000
	s_addc_u32 s27, s21, -1
	s_add_u32 s26, s26, s98
	s_addc_u32 s27, s27, s99
	s_sub_i32 s89, 0, s98
	s_not_b32 s90, s99
	s_cmp_eq_u32 s57, 12
	s_cselect_b32 s29, s13, s27
	s_cselect_b32 s28, s53, s26
	s_cselect_b32 s27, s11, s56
	s_cselect_b32 s26, s54, s55
	s_cselect_b32 s100, s89, s98
	s_cselect_b32 s101, s90, s99
	s_add_i32 m0, s19, 0xc000
	ds_read_b128 v[168:171], v150
	ds_read_b128 v[172:175], v150 offset:1024
	ds_read_b128 v[176:179], v150 offset:2048
	ds_read_b128 v[180:183], v150 offset:3072
	ds_read_b128 v[184:187], v150 offset:4096
	ds_read_b128 v[188:191], v150 offset:5120
	ds_read_b128 v[192:195], v150 offset:6144
	ds_read_b128 v[196:199], v150 offset:7168
	global_load_lds_dwordx4 v136, s[20:21]
	s_add_i32 m0, s19, 0xe000
	s_nop 0
	global_load_lds_dwordx4 v138, s[20:21]
	s_waitcnt lgkmcnt(8)
	s_barrier
	s_waitcnt lgkmcnt(0)
	s_waitcnt lgkmcnt(0)
	v_mfma_f32_16x16x32_bf16 v[124:127], v[152:155], v[168:171], 0
	v_mfma_f32_16x16x32_bf16 v[120:123], v[160:163], v[168:171], 0
	v_mfma_f32_16x16x32_bf16 v[108:111], v[152:155], v[176:179], 0
	v_mfma_f32_16x16x32_bf16 v[104:107], v[160:163], v[176:179], 0
	v_mfma_f32_16x16x32_bf16 v[92:95], v[152:155], v[184:187], 0
	v_mfma_f32_16x16x32_bf16 v[88:91], v[160:163], v[184:187], 0
	v_mfma_f32_16x16x32_bf16 v[76:79], v[152:155], v[192:195], 0
	v_mfma_f32_16x16x32_bf16 v[72:75], v[160:163], v[192:195], 0
	v_mfma_f32_16x16x32_bf16 v[124:127], v[156:159], v[172:175], v[124:127]
	v_mfma_f32_16x16x32_bf16 v[120:123], v[164:167], v[172:175], v[120:123]
	v_mfma_f32_16x16x32_bf16 v[108:111], v[156:159], v[180:183], v[108:111]
	v_mfma_f32_16x16x32_bf16 v[104:107], v[164:167], v[180:183], v[104:107]
	v_mfma_f32_16x16x32_bf16 v[92:95], v[156:159], v[188:191], v[92:95]
	v_mfma_f32_16x16x32_bf16 v[88:91], v[164:167], v[188:191], v[88:91]
	v_mfma_f32_16x16x32_bf16 v[76:79], v[156:159], v[196:199], v[76:79]
	v_mfma_f32_16x16x32_bf16 v[72:75], v[164:167], v[196:199], v[72:75]
	s_barrier
	s_add_i32 s58, s47, s38
	s_add_u32 s80, s26, s100
	s_addc_u32 s81, s27, s101
	s_mov_b32 m0, s58
	ds_read_b128 v[200:203], v151
	ds_read_b128 v[204:207], v151 offset:1024
	ds_read_b128 v[208:211], v151 offset:2048
	ds_read_b128 v[212:215], v151 offset:3072
	global_load_lds_dwordx4 v132, s[26:27]
	s_add_i32 m0, s58, 0x2000
	s_nop 0
	global_load_lds_dwordx4 v128, s[26:27]
	s_cmp_lg_u32 s94, 0
	s_cbranch_scc1 .Lpw131_0a
	s_waitcnt vmcnt(10)
	s_branch .Lpw131_0b

.Lpw131_0b:
	s_barrier
	s_waitcnt lgkmcnt(0)
	s_waitcnt lgkmcnt(0)
	v_mfma_f32_16x16x32_bf16 v[116:119], v[200:203], v[168:171], 0
	v_mfma_f32_16x16x32_bf16 v[112:115], v[208:211], v[168:171], 0
	v_mfma_f32_16x16x32_bf16 v[100:103], v[200:203], v[176:179], 0
	v_mfma_f32_16x16x32_bf16 v[96:99], v[208:211], v[176:179], 0
	v_mfma_f32_16x16x32_bf16 v[84:87], v[200:203], v[184:187], 0
	v_mfma_f32_16x16x32_bf16 v[80:83], v[208:211], v[184:187], 0
	v_mfma_f32_16x16x32_bf16 v[68:71], v[200:203], v[192:195], 0
	v_mfma_f32_16x16x32_bf16 v[64:67], v[208:211], v[192:195], 0
	v_mfma_f32_16x16x32_bf16 v[116:119], v[204:207], v[172:175], v[116:119]
	v_mfma_f32_16x16x32_bf16 v[112:115], v[212:215], v[172:175], v[112:115]
	v_mfma_f32_16x16x32_bf16 v[100:103], v[204:207], v[180:183], v[100:103]
	v_mfma_f32_16x16x32_bf16 v[96:99], v[212:215], v[180:183], v[96:99]
	v_mfma_f32_16x16x32_bf16 v[84:87], v[204:207], v[188:191], v[84:87]
	v_mfma_f32_16x16x32_bf16 v[80:83], v[212:215], v[188:191], v[80:83]
	v_mfma_f32_16x16x32_bf16 v[68:71], v[204:207], v[196:199], v[68:71]
	v_mfma_f32_16x16x32_bf16 v[64:67], v[212:215], v[196:199], v[64:67]
	s_mov_b32 m0, s19
	s_add_u32 s82, s28, s100
	s_addc_u32 s83, s29, s101
	s_barrier
	ds_read_b128 v[168:171], v150 offset:16384
	ds_read_b128 v[172:175], v150 offset:17408
	ds_read_b128 v[176:179], v150 offset:18432
	ds_read_b128 v[180:183], v150 offset:19456
	ds_read_b128 v[184:187], v150 offset:20480
	ds_read_b128 v[188:191], v150 offset:21504
	ds_read_b128 v[192:195], v150 offset:22528
	ds_read_b128 v[196:199], v150 offset:23552
	global_load_lds_dwordx4 v134, s[28:29]
	s_mov_b32 m0, s42
	s_nop 0
	global_load_lds_dwordx4 v130, s[28:29]
	s_barrier
	s_waitcnt lgkmcnt(0)
	s_waitcnt lgkmcnt(0)
	v_mfma_f32_16x16x32_bf16 v[60:63], v[152:155], v[168:171], 0
	v_mfma_f32_16x16x32_bf16 v[56:59], v[160:163], v[168:171], 0
	v_mfma_f32_16x16x32_bf16 v[44:47], v[152:155], v[176:179], 0
	v_mfma_f32_16x16x32_bf16 v[40:43], v[160:163], v[176:179], 0
	v_mfma_f32_16x16x32_bf16 v[28:31], v[152:155], v[184:187], 0
	v_mfma_f32_16x16x32_bf16 v[24:27], v[160:163], v[184:187], 0
	v_mfma_f32_16x16x32_bf16 v[12:15], v[152:155], v[192:195], 0
	v_mfma_f32_16x16x32_bf16 v[8:11], v[160:163], v[192:195], 0
	v_mfma_f32_16x16x32_bf16 v[60:63], v[156:159], v[172:175], v[60:63]
	v_mfma_f32_16x16x32_bf16 v[56:59], v[164:167], v[172:175], v[56:59]
	v_mfma_f32_16x16x32_bf16 v[44:47], v[156:159], v[180:183], v[44:47]
	v_mfma_f32_16x16x32_bf16 v[40:43], v[164:167], v[180:183], v[40:43]
	v_mfma_f32_16x16x32_bf16 v[28:31], v[156:159], v[188:191], v[28:31]
	v_mfma_f32_16x16x32_bf16 v[24:27], v[164:167], v[188:191], v[24:27]
	v_mfma_f32_16x16x32_bf16 v[12:15], v[156:159], v[196:199], v[12:15]
	v_mfma_f32_16x16x32_bf16 v[8:11], v[164:167], v[196:199], v[8:11]
	s_barrier
	s_add_u32 s58, s26, 0x40000
	s_addc_u32 s59, s27, 0
	s_add_i32 s60, s48, s38
	s_mov_b32 m0, s60
	s_nop 0
	global_load_lds_dwordx4 v132, s[58:59]
	s_add_i32 m0, s60, 0x2000
	s_nop 0
	global_load_lds_dwordx4 v128, s[58:59]
	s_cmp_lg_u32 s94, 0
	s_cbranch_scc1 .Lpw131_1a
	s_waitcnt vmcnt(8)
	s_branch .Lpw131_1b

.Lg131_mid:
	ds_read_b128 v[152:155], v164
	ds_read_b128 v[156:159], v164 offset:1024
	ds_read_b128 v[160:163], v164 offset:2048
	ds_read_b128 v[164:167], v164 offset:3072
	s_add_u32 s28, s28, 0x40000
	s_addc_u32 s29, s29, 0
	s_mov_b32 m0, s43
	ds_read_b128 v[168:171], v150 offset:32768
	ds_read_b128 v[172:175], v150 offset:33792
	ds_read_b128 v[176:179], v150 offset:34816
	ds_read_b128 v[180:183], v150 offset:35840
	ds_read_b128 v[184:187], v150 offset:36864
	ds_read_b128 v[188:191], v150 offset:37888
	ds_read_b128 v[192:195], v150 offset:38912
	ds_read_b128 v[196:199], v150 offset:39936
	global_load_lds_dwordx4 v134, s[28:29]
	s_mov_b32 m0, s44
	s_nop 0
	global_load_lds_dwordx4 v130, s[28:29]
	s_waitcnt lgkmcnt(8)
	s_barrier
	s_waitcnt lgkmcnt(0)
	s_waitcnt lgkmcnt(0)
	v_mfma_f32_16x16x32_bf16 v[124:127], v[152:155], v[168:171], v[124:127]
	v_mfma_f32_16x16x32_bf16 v[120:123], v[160:163], v[168:171], v[120:123]
	v_mfma_f32_16x16x32_bf16 v[108:111], v[152:155], v[176:179], v[108:111]
	v_mfma_f32_16x16x32_bf16 v[104:107], v[160:163], v[176:179], v[104:107]
	v_mfma_f32_16x16x32_bf16 v[92:95], v[152:155], v[184:187], v[92:95]
	v_mfma_f32_16x16x32_bf16 v[88:91], v[160:163], v[184:187], v[88:91]
	v_mfma_f32_16x16x32_bf16 v[76:79], v[152:155], v[192:195], v[76:79]
	v_mfma_f32_16x16x32_bf16 v[72:75], v[160:163], v[192:195], v[72:75]
	v_mfma_f32_16x16x32_bf16 v[124:127], v[156:159], v[172:175], v[124:127]
	v_mfma_f32_16x16x32_bf16 v[120:123], v[164:167], v[172:175], v[120:123]
	v_mfma_f32_16x16x32_bf16 v[108:111], v[156:159], v[180:183], v[108:111]
	v_mfma_f32_16x16x32_bf16 v[104:107], v[164:167], v[180:183], v[104:107]
	v_mfma_f32_16x16x32_bf16 v[92:95], v[156:159], v[188:191], v[92:95]
	v_mfma_f32_16x16x32_bf16 v[88:91], v[164:167], v[188:191], v[88:91]
	v_mfma_f32_16x16x32_bf16 v[76:79], v[156:159], v[196:199], v[76:79]
	v_mfma_f32_16x16x32_bf16 v[72:75], v[164:167], v[196:199], v[72:75]
	s_barrier
	s_add_i32 s28, 0, 0x1c000
	s_add_i32 s29, s58, s38
	v_add_u32_e32 v212, s28, v145
	s_mov_b32 m0, s29
	ds_read_b128 v[200:203], v212
	ds_read_b128 v[204:207], v212 offset:1024
	ds_read_b128 v[208:211], v212 offset:2048
	ds_read_b128 v[212:215], v212 offset:3072
	global_load_lds_dwordx4 v132, s[80:81]
	s_add_i32 m0, s29, 0x2000
	s_nop 0
	global_load_lds_dwordx4 v128, s[80:81]
	s_waitcnt vmcnt(10)
	s_barrier
	s_waitcnt lgkmcnt(0)
	s_waitcnt lgkmcnt(0)
	v_mfma_f32_16x16x32_bf16 v[116:119], v[200:203], v[168:171], v[116:119]
	v_mfma_f32_16x16x32_bf16 v[112:115], v[208:211], v[168:171], v[112:115]
	v_mfma_f32_16x16x32_bf16 v[100:103], v[200:203], v[176:179], v[100:103]
	v_mfma_f32_16x16x32_bf16 v[96:99], v[208:211], v[176:179], v[96:99]
	v_mfma_f32_16x16x32_bf16 v[84:87], v[200:203], v[184:187], v[84:87]
	v_mfma_f32_16x16x32_bf16 v[80:83], v[208:211], v[184:187], v[80:83]
	v_mfma_f32_16x16x32_bf16 v[68:71], v[200:203], v[192:195], v[68:71]
	v_mfma_f32_16x16x32_bf16 v[64:67], v[208:211], v[192:195], v[64:67]
	v_mfma_f32_16x16x32_bf16 v[116:119], v[204:207], v[172:175], v[116:119]
	v_mfma_f32_16x16x32_bf16 v[112:115], v[212:215], v[172:175], v[112:115]
	v_mfma_f32_16x16x32_bf16 v[100:103], v[204:207], v[180:183], v[100:103]
	v_mfma_f32_16x16x32_bf16 v[96:99], v[212:215], v[180:183], v[96:99]
	v_mfma_f32_16x16x32_bf16 v[84:87], v[204:207], v[188:191], v[84:87]
	v_mfma_f32_16x16x32_bf16 v[80:83], v[212:215], v[188:191], v[80:83]
	v_mfma_f32_16x16x32_bf16 v[68:71], v[204:207], v[196:199], v[68:71]
	v_mfma_f32_16x16x32_bf16 v[64:67], v[212:215], v[196:199], v[64:67]
	s_mov_b32 m0, s45
	s_barrier
	ds_read_b128 v[168:171], v150 offset:49152
	ds_read_b128 v[172:175], v150 offset:50176
	ds_read_b128 v[176:179], v150 offset:51200
	ds_read_b128 v[180:183], v150 offset:52224
	ds_read_b128 v[184:187], v150 offset:53248
	ds_read_b128 v[188:191], v150 offset:54272
	ds_read_b128 v[192:195], v150 offset:55296
	ds_read_b128 v[196:199], v150 offset:56320
	global_load_lds_dwordx4 v134, s[82:83]
	s_mov_b32 m0, s46
	s_nop 0
	global_load_lds_dwordx4 v130, s[82:83]
	s_barrier
	s_waitcnt lgkmcnt(0)
	s_waitcnt lgkmcnt(0)
	v_mfma_f32_16x16x32_bf16 v[60:63], v[152:155], v[168:171], v[60:63]
	v_mfma_f32_16x16x32_bf16 v[56:59], v[160:163], v[168:171], v[56:59]
	v_mfma_f32_16x16x32_bf16 v[44:47], v[152:155], v[176:179], v[44:47]
	v_mfma_f32_16x16x32_bf16 v[40:43], v[160:163], v[176:179], v[40:43]
	v_mfma_f32_16x16x32_bf16 v[28:31], v[152:155], v[184:187], v[28:31]
	v_mfma_f32_16x16x32_bf16 v[24:27], v[160:163], v[184:187], v[24:27]
	v_mfma_f32_16x16x32_bf16 v[12:15], v[152:155], v[192:195], v[12:15]
	v_mfma_f32_16x16x32_bf16 v[8:11], v[160:163], v[192:195], v[8:11]
	v_mfma_f32_16x16x32_bf16 v[60:63], v[156:159], v[172:175], v[60:63]
	v_mfma_f32_16x16x32_bf16 v[56:59], v[164:167], v[172:175], v[56:59]
	v_mfma_f32_16x16x32_bf16 v[44:47], v[156:159], v[180:183], v[44:47]
	v_mfma_f32_16x16x32_bf16 v[40:43], v[164:167], v[180:183], v[40:43]
	v_mfma_f32_16x16x32_bf16 v[28:31], v[156:159], v[188:191], v[28:31]
	v_mfma_f32_16x16x32_bf16 v[24:27], v[164:167], v[188:191], v[24:27]
	v_mfma_f32_16x16x32_bf16 v[12:15], v[156:159], v[196:199], v[12:15]
	v_mfma_f32_16x16x32_bf16 v[8:11], v[164:167], v[196:199], v[8:11]
	s_barrier
	s_add_u32 s26, s26, 0x40000
	s_addc_u32 s27, s27, 0
	s_add_u32 s26, s26, s100
	s_addc_u32 s27, s27, s101
	s_add_i32 s28, s28, s38
	s_mov_b32 m0, s28
	s_nop 0
	global_load_lds_dwordx4 v132, s[26:27]
	s_add_i32 m0, s28, 0x2000
	s_nop 0
	global_load_lds_dwordx4 v128, s[26:27]
	s_waitcnt vmcnt(8)
	s_barrier
	v_mfma_f32_16x16x32_bf16 v[52:55], v[200:203], v[168:171], v[52:55]
	v_mfma_f32_16x16x32_bf16 v[48:51], v[208:211], v[168:171], v[48:51]
	v_mfma_f32_16x16x32_bf16 v[36:39], v[200:203], v[176:179], v[36:39]
	v_mfma_f32_16x16x32_bf16 v[32:35], v[208:211], v[176:179], v[32:35]
	v_mfma_f32_16x16x32_bf16 v[20:23], v[200:203], v[184:187], v[20:23]
	v_mfma_f32_16x16x32_bf16 v[16:19], v[208:211], v[184:187], v[16:19]
	v_mfma_f32_16x16x32_bf16 v[4:7], v[200:203], v[192:195], v[4:7]
	v_mfma_f32_16x16x32_bf16 v[0:3], v[208:211], v[192:195], v[0:3]
	v_mfma_f32_16x16x32_bf16 v[52:55], v[204:207], v[172:175], v[52:55]
	v_mfma_f32_16x16x32_bf16 v[48:51], v[212:215], v[172:175], v[48:51]
	v_mfma_f32_16x16x32_bf16 v[36:39], v[204:207], v[180:183], v[36:39]
	v_mfma_f32_16x16x32_bf16 v[32:35], v[212:215], v[180:183], v[32:35]
	v_mfma_f32_16x16x32_bf16 v[20:23], v[204:207], v[188:191], v[20:23]
	v_mfma_f32_16x16x32_bf16 v[16:19], v[212:215], v[188:191], v[16:19]
	v_mfma_f32_16x16x32_bf16 v[4:7], v[204:207], v[196:199], v[4:7]
	v_mfma_f32_16x16x32_bf16 v[0:3], v[212:215], v[196:199], v[0:3]
	s_add_i32 s57, s57, 2
	s_lshl_b32 s88, s98, 1
	s_add_u32 s20, s20, s88
	s_addc_u32 s21, s21, s99
	s_add_u32 s55, s55, s88
	s_addc_u32 s56, s56, s99
	s_cmp_gt_u32 s57, 13
	s_barrier
	s_cbranch_scc0 .LBB0_131
	s_setprio 0
	s_mov_b32 s94, 1
	v_lshl_add_u32 v180, s51, 10, v147
	ds_read2_b32 v[152:153], v180 offset1:16
	ds_read2_b32 v[154:155], v180 offset0:32 offset1:48
	ds_read2_b32 v[156:157], v180 offset0:128 offset1:144
	ds_read2_b32 v[158:159], v180 offset0:160 offset1:176
	v_lshl_or_b32 v181, s52, 7, v148
	v_lshl_add_u32 v182, s18, 8, v144
	s_and_b64 vcc, exec, s[4:5]
	s_mov_b32 s52, s10
	s_mov_b32 s18, s12
	s_mov_b64 s[26:27], s[16:17]
	s_mov_b32 s51, s50
	s_mov_b64 s[20:21], s[14:15]
	v_mul_u32_u24_e32 v183, s49, v182
	v_lshl_add_u32 v183, v181, 1, v183
	s_waitcnt lgkmcnt(0)
	v_mul_f32_e32 v176, 0xbfb8aa3b, v152
	v_mul_f32_e32 v177, v152, v152
	v_rcp_f32_e32 v178, v177
	v_pk_mul_f32 v[160:161], v[124:125], v[176:177] op_sel_hi:[1,0]
	v_pk_mul_f32 v[162:163], v[126:127], v[176:177] op_sel_hi:[1,0]
	v_pk_mul_f32 v[164:165], v[120:121], v[176:177] op_sel_hi:[1,0]
	v_pk_mul_f32 v[166:167], v[122:123], v[176:177] op_sel_hi:[1,0]
	v_exp_f32_e32 v160, v160
	v_exp_f32_e32 v161, v161
	v_exp_f32_e32 v162, v162
	v_exp_f32_e32 v163, v163
	v_exp_f32_e32 v164, v164
	v_exp_f32_e32 v165, v165
	v_exp_f32_e32 v166, v166
	v_exp_f32_e32 v167, v167
	v_pk_fma_f32 v[160:161], v[160:161], v[178:179], v[178:179] op_sel_hi:[1,0,0]
	v_pk_fma_f32 v[162:163], v[162:163], v[178:179], v[178:179] op_sel_hi:[1,0,0]
	v_pk_fma_f32 v[164:165], v[164:165], v[178:179], v[178:179] op_sel_hi:[1,0,0]
	v_pk_fma_f32 v[166:167], v[166:167], v[178:179], v[178:179] op_sel_hi:[1,0,0]
	v_rcp_f32_e32 v160, v160
	v_rcp_f32_e32 v161, v161
	v_rcp_f32_e32 v162, v162
	v_rcp_f32_e32 v163, v163
	v_rcp_f32_e32 v164, v164
	v_rcp_f32_e32 v165, v165
	v_rcp_f32_e32 v166, v166
	v_rcp_f32_e32 v167, v167
	v_pk_mul_f32 v[124:125], v[124:125], v[116:117]
	v_pk_mul_f32 v[126:127], v[126:127], v[118:119]
	v_pk_mul_f32 v[120:121], v[120:121], v[112:113]
	v_pk_mul_f32 v[122:123], v[122:123], v[114:115]
	v_pk_mul_f32 v[124:125], v[124:125], v[160:161]
	v_pk_mul_f32 v[126:127], v[126:127], v[162:163]
	v_pk_mul_f32 v[120:121], v[120:121], v[164:165]
	v_pk_mul_f32 v[122:123], v[122:123], v[166:167]
	v_cvt_pk_bf16_f32 v168, v124, v125
	v_cvt_pk_bf16_f32 v169, v126, v127
	v_cvt_pk_bf16_f32 v170, v120, v121
	v_cvt_pk_bf16_f32 v171, v122, v123
	global_store_dwordx4 v183, v[168:171], s[6:7]
	s_cmpk_gt_u32 s37, 0xff
	s_cbranch_scc1 .Lg131_nox
	s_barrier
	s_setprio 1

.Lg893_noy:
	ds_read_b128 v[152:155], v148
	ds_read_b128 v[156:159], v148 offset:1024
	ds_read_b128 v[160:163], v148 offset:2048
	ds_read_b128 v[164:167], v148 offset:3072
	s_add_u32 s26, s20, 0xfffc0000
	s_addc_u32 s27, s21, -1
	s_add_u32 s26, s26, s98
	s_addc_u32 s27, s27, s99
	s_sub_i32 s89, 0, s98
	s_not_b32 s90, s99
	s_cmp_eq_u32 s57, 12
	s_cselect_b32 s29, s13, s27
	s_cselect_b32 s28, s53, s26
	s_cselect_b32 s27, s11, s56
	s_cselect_b32 s26, s54, s55
	s_cselect_b32 s100, s89, s98
	s_cselect_b32 s101, s90, s99
	s_add_i32 m0, s19, 0xc000
	ds_read_b128 v[168:171], v149
	ds_read_b128 v[172:175], v149 offset:1024
	ds_read_b128 v[176:179], v149 offset:2048
	ds_read_b128 v[180:183], v149 offset:3072
	ds_read_b128 v[184:187], v149 offset:4096
	ds_read_b128 v[188:191], v149 offset:5120
	ds_read_b128 v[192:195], v149 offset:6144
	ds_read_b128 v[196:199], v149 offset:7168
	global_load_lds_dwordx4 v136, s[20:21]
	s_add_i32 m0, s19, 0xe000
	s_nop 0
	global_load_lds_dwordx4 v138, s[20:21]
	s_waitcnt lgkmcnt(8)
	s_barrier
	s_waitcnt lgkmcnt(0)
	s_waitcnt lgkmcnt(0)
	v_mfma_f32_16x16x32_bf16 v[124:127], v[152:155], v[168:171], 0
	v_mfma_f32_16x16x32_bf16 v[120:123], v[160:163], v[168:171], 0
	v_mfma_f32_16x16x32_bf16 v[108:111], v[152:155], v[176:179], 0
	v_mfma_f32_16x16x32_bf16 v[104:107], v[160:163], v[176:179], 0
	v_mfma_f32_16x16x32_bf16 v[92:95], v[152:155], v[184:187], 0
	v_mfma_f32_16x16x32_bf16 v[88:91], v[160:163], v[184:187], 0
	v_mfma_f32_16x16x32_bf16 v[76:79], v[152:155], v[192:195], 0
	v_mfma_f32_16x16x32_bf16 v[72:75], v[160:163], v[192:195], 0
	v_mfma_f32_16x16x32_bf16 v[124:127], v[156:159], v[172:175], v[124:127]
	v_mfma_f32_16x16x32_bf16 v[120:123], v[164:167], v[172:175], v[120:123]
	v_mfma_f32_16x16x32_bf16 v[108:111], v[156:159], v[180:183], v[108:111]
	v_mfma_f32_16x16x32_bf16 v[104:107], v[164:167], v[180:183], v[104:107]
	v_mfma_f32_16x16x32_bf16 v[92:95], v[156:159], v[188:191], v[92:95]
	v_mfma_f32_16x16x32_bf16 v[88:91], v[164:167], v[188:191], v[88:91]
	v_mfma_f32_16x16x32_bf16 v[76:79], v[156:159], v[196:199], v[76:79]
	v_mfma_f32_16x16x32_bf16 v[72:75], v[164:167], v[196:199], v[72:75]
	s_barrier
	s_add_i32 s58, s47, s31
	s_add_u32 s80, s26, s100
	s_addc_u32 s81, s27, s101
	s_mov_b32 m0, s58
	ds_read_b128 v[200:203], v150
	ds_read_b128 v[204:207], v150 offset:1024
	ds_read_b128 v[208:211], v150 offset:2048
	ds_read_b128 v[212:215], v150 offset:3072
	global_load_lds_dwordx4 v132, s[26:27]
	s_add_i32 m0, s58, 0x2000
	s_nop 0
	global_load_lds_dwordx4 v128, s[26:27]
	s_cmp_lg_u32 s94, 0
	s_cbranch_scc1 .Lpw893_0a
	s_waitcnt vmcnt(10)
	s_branch .Lpw893_0b

.Lpw893_0b:
	s_barrier
	s_waitcnt lgkmcnt(0)
	s_waitcnt lgkmcnt(0)
	v_mfma_f32_16x16x32_bf16 v[116:119], v[200:203], v[168:171], 0
	v_mfma_f32_16x16x32_bf16 v[112:115], v[208:211], v[168:171], 0
	v_mfma_f32_16x16x32_bf16 v[100:103], v[200:203], v[176:179], 0
	v_mfma_f32_16x16x32_bf16 v[96:99], v[208:211], v[176:179], 0
	v_mfma_f32_16x16x32_bf16 v[84:87], v[200:203], v[184:187], 0
	v_mfma_f32_16x16x32_bf16 v[80:83], v[208:211], v[184:187], 0
	v_mfma_f32_16x16x32_bf16 v[68:71], v[200:203], v[192:195], 0
	v_mfma_f32_16x16x32_bf16 v[64:67], v[208:211], v[192:195], 0
	v_mfma_f32_16x16x32_bf16 v[116:119], v[204:207], v[172:175], v[116:119]
	v_mfma_f32_16x16x32_bf16 v[112:115], v[212:215], v[172:175], v[112:115]
	v_mfma_f32_16x16x32_bf16 v[100:103], v[204:207], v[180:183], v[100:103]
	v_mfma_f32_16x16x32_bf16 v[96:99], v[212:215], v[180:183], v[96:99]
	v_mfma_f32_16x16x32_bf16 v[84:87], v[204:207], v[188:191], v[84:87]
	v_mfma_f32_16x16x32_bf16 v[80:83], v[212:215], v[188:191], v[80:83]
	v_mfma_f32_16x16x32_bf16 v[68:71], v[204:207], v[196:199], v[68:71]
	v_mfma_f32_16x16x32_bf16 v[64:67], v[212:215], v[196:199], v[64:67]
	s_mov_b32 m0, s19
	s_add_u32 s82, s28, s100
	s_addc_u32 s83, s29, s101
	s_barrier
	ds_read_b128 v[168:171], v149 offset:16384
	ds_read_b128 v[172:175], v149 offset:17408
	ds_read_b128 v[176:179], v149 offset:18432
	ds_read_b128 v[180:183], v149 offset:19456
	ds_read_b128 v[184:187], v149 offset:20480
	ds_read_b128 v[188:191], v149 offset:21504
	ds_read_b128 v[192:195], v149 offset:22528
	ds_read_b128 v[196:199], v149 offset:23552
	global_load_lds_dwordx4 v134, s[28:29]
	s_mov_b32 m0, s42
	s_nop 0
	global_load_lds_dwordx4 v130, s[28:29]
	s_barrier
	s_waitcnt lgkmcnt(0)
	s_waitcnt lgkmcnt(0)
	v_mfma_f32_16x16x32_bf16 v[60:63], v[152:155], v[168:171], 0
	v_mfma_f32_16x16x32_bf16 v[56:59], v[160:163], v[168:171], 0
	v_mfma_f32_16x16x32_bf16 v[44:47], v[152:155], v[176:179], 0
	v_mfma_f32_16x16x32_bf16 v[40:43], v[160:163], v[176:179], 0
	v_mfma_f32_16x16x32_bf16 v[28:31], v[152:155], v[184:187], 0
	v_mfma_f32_16x16x32_bf16 v[24:27], v[160:163], v[184:187], 0
	v_mfma_f32_16x16x32_bf16 v[12:15], v[152:155], v[192:195], 0
	v_mfma_f32_16x16x32_bf16 v[8:11], v[160:163], v[192:195], 0
	v_mfma_f32_16x16x32_bf16 v[60:63], v[156:159], v[172:175], v[60:63]
	v_mfma_f32_16x16x32_bf16 v[56:59], v[164:167], v[172:175], v[56:59]
	v_mfma_f32_16x16x32_bf16 v[44:47], v[156:159], v[180:183], v[44:47]
	v_mfma_f32_16x16x32_bf16 v[40:43], v[164:167], v[180:183], v[40:43]
	v_mfma_f32_16x16x32_bf16 v[28:31], v[156:159], v[188:191], v[28:31]
	v_mfma_f32_16x16x32_bf16 v[24:27], v[164:167], v[188:191], v[24:27]
	v_mfma_f32_16x16x32_bf16 v[12:15], v[156:159], v[196:199], v[12:15]
	v_mfma_f32_16x16x32_bf16 v[8:11], v[164:167], v[196:199], v[8:11]
	s_barrier
	s_add_u32 s58, s26, 0x40000
	s_addc_u32 s59, s27, 0
	s_add_i32 s60, s48, s31
	s_mov_b32 m0, s60
	s_nop 0
	global_load_lds_dwordx4 v132, s[58:59]
	s_add_i32 m0, s60, 0x2000
	s_nop 0
	global_load_lds_dwordx4 v128, s[58:59]
	s_cmp_lg_u32 s94, 0
	s_cbranch_scc1 .Lpw893_1a
	s_waitcnt vmcnt(8)
	s_branch .Lpw893_1b

.Lg893_mid:
	ds_read_b128 v[152:155], v151
	ds_read_b128 v[156:159], v151 offset:1024
	ds_read_b128 v[160:163], v151 offset:2048
	ds_read_b128 v[164:167], v151 offset:3072
	s_add_u32 s28, s28, 0x40000
	s_addc_u32 s29, s29, 0
	s_mov_b32 m0, s43
	ds_read_b128 v[168:171], v149 offset:32768
	ds_read_b128 v[172:175], v149 offset:33792
	ds_read_b128 v[176:179], v149 offset:34816
	ds_read_b128 v[180:183], v149 offset:35840
	ds_read_b128 v[184:187], v149 offset:36864
	ds_read_b128 v[188:191], v149 offset:37888
	ds_read_b128 v[192:195], v149 offset:38912
	ds_read_b128 v[196:199], v149 offset:39936
	global_load_lds_dwordx4 v134, s[28:29]
	s_mov_b32 m0, s44
	s_nop 0
	global_load_lds_dwordx4 v130, s[28:29]
	s_waitcnt lgkmcnt(8)
	s_barrier
	s_waitcnt lgkmcnt(0)
	s_waitcnt lgkmcnt(0)
	v_mfma_f32_16x16x32_bf16 v[124:127], v[152:155], v[168:171], v[124:127]
	v_mfma_f32_16x16x32_bf16 v[120:123], v[160:163], v[168:171], v[120:123]
	v_mfma_f32_16x16x32_bf16 v[108:111], v[152:155], v[176:179], v[108:111]
	v_mfma_f32_16x16x32_bf16 v[104:107], v[160:163], v[176:179], v[104:107]
	v_mfma_f32_16x16x32_bf16 v[92:95], v[152:155], v[184:187], v[92:95]
	v_mfma_f32_16x16x32_bf16 v[88:91], v[160:163], v[184:187], v[88:91]
	v_mfma_f32_16x16x32_bf16 v[76:79], v[152:155], v[192:195], v[76:79]
	v_mfma_f32_16x16x32_bf16 v[72:75], v[160:163], v[192:195], v[72:75]
	v_mfma_f32_16x16x32_bf16 v[124:127], v[156:159], v[172:175], v[124:127]
	v_mfma_f32_16x16x32_bf16 v[120:123], v[164:167], v[172:175], v[120:123]
	v_mfma_f32_16x16x32_bf16 v[108:111], v[156:159], v[180:183], v[108:111]
	v_mfma_f32_16x16x32_bf16 v[104:107], v[164:167], v[180:183], v[104:107]
	v_mfma_f32_16x16x32_bf16 v[92:95], v[156:159], v[188:191], v[92:95]
	v_mfma_f32_16x16x32_bf16 v[88:91], v[164:167], v[188:191], v[88:91]
	v_mfma_f32_16x16x32_bf16 v[76:79], v[156:159], v[196:199], v[76:79]
	v_mfma_f32_16x16x32_bf16 v[72:75], v[164:167], v[196:199], v[72:75]
	s_barrier
	s_add_i32 s28, 0, 0x1c000
	s_add_i32 s29, s58, s31
	v_add_u32_e32 v151, s28, v145
	s_mov_b32 m0, s29
	ds_read_b128 v[200:203], v151
	ds_read_b128 v[204:207], v151 offset:1024
	ds_read_b128 v[208:211], v151 offset:2048
	ds_read_b128 v[212:215], v151 offset:3072
	global_load_lds_dwordx4 v132, s[80:81]
	s_add_i32 m0, s29, 0x2000
	s_nop 0
	global_load_lds_dwordx4 v128, s[80:81]
	s_waitcnt vmcnt(10)
	s_barrier
	s_waitcnt lgkmcnt(0)
	s_waitcnt lgkmcnt(0)
	v_mfma_f32_16x16x32_bf16 v[116:119], v[200:203], v[168:171], v[116:119]
	v_mfma_f32_16x16x32_bf16 v[112:115], v[208:211], v[168:171], v[112:115]
	v_mfma_f32_16x16x32_bf16 v[100:103], v[200:203], v[176:179], v[100:103]
	v_mfma_f32_16x16x32_bf16 v[96:99], v[208:211], v[176:179], v[96:99]
	v_mfma_f32_16x16x32_bf16 v[84:87], v[200:203], v[184:187], v[84:87]
	v_mfma_f32_16x16x32_bf16 v[80:83], v[208:211], v[184:187], v[80:83]
	v_mfma_f32_16x16x32_bf16 v[68:71], v[200:203], v[192:195], v[68:71]
	v_mfma_f32_16x16x32_bf16 v[64:67], v[208:211], v[192:195], v[64:67]
	v_mfma_f32_16x16x32_bf16 v[116:119], v[204:207], v[172:175], v[116:119]
	v_mfma_f32_16x16x32_bf16 v[112:115], v[212:215], v[172:175], v[112:115]
	v_mfma_f32_16x16x32_bf16 v[100:103], v[204:207], v[180:183], v[100:103]
	v_mfma_f32_16x16x32_bf16 v[96:99], v[212:215], v[180:183], v[96:99]
	v_mfma_f32_16x16x32_bf16 v[84:87], v[204:207], v[188:191], v[84:87]
	v_mfma_f32_16x16x32_bf16 v[80:83], v[212:215], v[188:191], v[80:83]
	v_mfma_f32_16x16x32_bf16 v[68:71], v[204:207], v[196:199], v[68:71]
	v_mfma_f32_16x16x32_bf16 v[64:67], v[212:215], v[196:199], v[64:67]
	s_mov_b32 m0, s45
	s_barrier
	ds_read_b128 v[168:171], v149 offset:49152
	ds_read_b128 v[172:175], v149 offset:50176
	ds_read_b128 v[176:179], v149 offset:51200
	ds_read_b128 v[180:183], v149 offset:52224
	ds_read_b128 v[184:187], v149 offset:53248
	ds_read_b128 v[188:191], v149 offset:54272
	ds_read_b128 v[192:195], v149 offset:55296
	ds_read_b128 v[196:199], v149 offset:56320
	global_load_lds_dwordx4 v134, s[82:83]
	s_mov_b32 m0, s46
	s_nop 0
	global_load_lds_dwordx4 v130, s[82:83]
	s_barrier
	s_waitcnt lgkmcnt(0)
	s_waitcnt lgkmcnt(0)
	v_mfma_f32_16x16x32_bf16 v[60:63], v[152:155], v[168:171], v[60:63]
	v_mfma_f32_16x16x32_bf16 v[56:59], v[160:163], v[168:171], v[56:59]
	v_mfma_f32_16x16x32_bf16 v[44:47], v[152:155], v[176:179], v[44:47]
	v_mfma_f32_16x16x32_bf16 v[40:43], v[160:163], v[176:179], v[40:43]
	v_mfma_f32_16x16x32_bf16 v[28:31], v[152:155], v[184:187], v[28:31]
	v_mfma_f32_16x16x32_bf16 v[24:27], v[160:163], v[184:187], v[24:27]
	v_mfma_f32_16x16x32_bf16 v[12:15], v[152:155], v[192:195], v[12:15]
	v_mfma_f32_16x16x32_bf16 v[8:11], v[160:163], v[192:195], v[8:11]
	v_mfma_f32_16x16x32_bf16 v[60:63], v[156:159], v[172:175], v[60:63]
	v_mfma_f32_16x16x32_bf16 v[56:59], v[164:167], v[172:175], v[56:59]
	v_mfma_f32_16x16x32_bf16 v[44:47], v[156:159], v[180:183], v[44:47]
	v_mfma_f32_16x16x32_bf16 v[40:43], v[164:167], v[180:183], v[40:43]
	v_mfma_f32_16x16x32_bf16 v[28:31], v[156:159], v[188:191], v[28:31]
	v_mfma_f32_16x16x32_bf16 v[24:27], v[164:167], v[188:191], v[24:27]
	v_mfma_f32_16x16x32_bf16 v[12:15], v[156:159], v[196:199], v[12:15]
	v_mfma_f32_16x16x32_bf16 v[8:11], v[164:167], v[196:199], v[8:11]
	s_barrier
	s_add_u32 s26, s26, 0x40000
	s_addc_u32 s27, s27, 0
	s_add_u32 s26, s26, s100
	s_addc_u32 s27, s27, s101
	s_add_i32 s28, s28, s31
	s_mov_b32 m0, s28
	s_nop 0
	global_load_lds_dwordx4 v132, s[26:27]
	s_add_i32 m0, s28, 0x2000
	s_nop 0
	global_load_lds_dwordx4 v128, s[26:27]
	s_waitcnt vmcnt(8)
	s_barrier
	v_mfma_f32_16x16x32_bf16 v[52:55], v[200:203], v[168:171], v[52:55]
	v_mfma_f32_16x16x32_bf16 v[48:51], v[208:211], v[168:171], v[48:51]
	v_mfma_f32_16x16x32_bf16 v[36:39], v[200:203], v[176:179], v[36:39]
	v_mfma_f32_16x16x32_bf16 v[32:35], v[208:211], v[176:179], v[32:35]
	v_mfma_f32_16x16x32_bf16 v[20:23], v[200:203], v[184:187], v[20:23]
	v_mfma_f32_16x16x32_bf16 v[16:19], v[208:211], v[184:187], v[16:19]
	v_mfma_f32_16x16x32_bf16 v[4:7], v[200:203], v[192:195], v[4:7]
	v_mfma_f32_16x16x32_bf16 v[0:3], v[208:211], v[192:195], v[0:3]
	v_mfma_f32_16x16x32_bf16 v[52:55], v[204:207], v[172:175], v[52:55]
	v_mfma_f32_16x16x32_bf16 v[48:51], v[212:215], v[172:175], v[48:51]
	v_mfma_f32_16x16x32_bf16 v[36:39], v[204:207], v[180:183], v[36:39]
	v_mfma_f32_16x16x32_bf16 v[32:35], v[212:215], v[180:183], v[32:35]
	v_mfma_f32_16x16x32_bf16 v[20:23], v[204:207], v[188:191], v[20:23]
	v_mfma_f32_16x16x32_bf16 v[16:19], v[212:215], v[188:191], v[16:19]
	v_mfma_f32_16x16x32_bf16 v[4:7], v[204:207], v[196:199], v[4:7]
	v_mfma_f32_16x16x32_bf16 v[0:3], v[212:215], v[196:199], v[0:3]
	s_add_i32 s57, s57, 2
	s_lshl_b32 s88, s98, 1
	s_add_u32 s20, s20, s88
	s_addc_u32 s21, s21, s99
	s_add_u32 s55, s55, s88
	s_addc_u32 s56, s56, s99
	s_cmp_gt_u32 s57, 13
	s_barrier
	s_cbranch_scc0 .LBB0_893
	s_setprio 0
	s_mov_b32 s94, 1
	v_lshl_add_u32 v180, s51, 10, v146
	ds_read2_b32 v[152:153], v180 offset1:16
	ds_read2_b32 v[154:155], v180 offset0:32 offset1:48
	ds_read2_b32 v[156:157], v180 offset0:128 offset1:144
	ds_read2_b32 v[158:159], v180 offset0:160 offset1:176
	v_lshl_or_b32 v181, s52, 7, v147
	v_lshl_add_u32 v182, s18, 8, v144
	s_and_b64 vcc, exec, s[4:5]
	s_mov_b32 s52, s10
	s_mov_b32 s18, s12
	s_mov_b64 s[26:27], s[16:17]
	s_mov_b32 s51, s50
	s_mov_b64 s[20:21], s[14:15]
	v_mul_u32_u24_e32 v183, s49, v182
	v_lshl_add_u32 v183, v181, 1, v183
	s_waitcnt lgkmcnt(0)
	v_mul_f32_e32 v176, 0xbfb8aa3b, v152
	v_mul_f32_e32 v177, v152, v152
	v_rcp_f32_e32 v178, v177
	v_pk_mul_f32 v[160:161], v[124:125], v[176:177] op_sel_hi:[1,0]
	v_pk_mul_f32 v[162:163], v[126:127], v[176:177] op_sel_hi:[1,0]
	v_pk_mul_f32 v[164:165], v[120:121], v[176:177] op_sel_hi:[1,0]
	v_pk_mul_f32 v[166:167], v[122:123], v[176:177] op_sel_hi:[1,0]
	v_exp_f32_e32 v160, v160
	v_exp_f32_e32 v161, v161
	v_exp_f32_e32 v162, v162
	v_exp_f32_e32 v163, v163
	v_exp_f32_e32 v164, v164
	v_exp_f32_e32 v165, v165
	v_exp_f32_e32 v166, v166
	v_exp_f32_e32 v167, v167
	v_pk_fma_f32 v[160:161], v[160:161], v[178:179], v[178:179] op_sel_hi:[1,0,0]
	v_pk_fma_f32 v[162:163], v[162:163], v[178:179], v[178:179] op_sel_hi:[1,0,0]
	v_pk_fma_f32 v[164:165], v[164:165], v[178:179], v[178:179] op_sel_hi:[1,0,0]
	v_pk_fma_f32 v[166:167], v[166:167], v[178:179], v[178:179] op_sel_hi:[1,0,0]
	v_rcp_f32_e32 v160, v160
	v_rcp_f32_e32 v161, v161
	v_rcp_f32_e32 v162, v162
	v_rcp_f32_e32 v163, v163
	v_rcp_f32_e32 v164, v164
	v_rcp_f32_e32 v165, v165
	v_rcp_f32_e32 v166, v166
	v_rcp_f32_e32 v167, v167
	v_pk_mul_f32 v[124:125], v[124:125], v[116:117]
	v_pk_mul_f32 v[126:127], v[126:127], v[118:119]
	v_pk_mul_f32 v[120:121], v[120:121], v[112:113]
	v_pk_mul_f32 v[122:123], v[122:123], v[114:115]
	v_pk_mul_f32 v[124:125], v[124:125], v[160:161]
	v_pk_mul_f32 v[126:127], v[126:127], v[162:163]
	v_pk_mul_f32 v[120:121], v[120:121], v[164:165]
	v_pk_mul_f32 v[122:123], v[122:123], v[166:167]
	v_cvt_pk_bf16_f32 v168, v124, v125
	v_cvt_pk_bf16_f32 v169, v126, v127
	v_cvt_pk_bf16_f32 v170, v120, v121
	v_cvt_pk_bf16_f32 v171, v122, v123
	global_store_dwordx4 v183, v[168:171], s[6:7]
	s_cmpk_gt_u32 s30, 0xff
	s_cbranch_scc1 .Lg893_nox
	s_barrier
	s_setprio 1
